# baseline (speedup 1.0000x reference)
; #define tidx() tidx_(wv_)
; template <typename TokF>
; __device__ __forceinline__ void stage_k(u16* Ks, int nk, TokF tokf, const u16* z, int ld, int col, bool rope, const float* tb, int wv_) {
;   for (int task = tidx(); task < nk * 4; task += NTHREADS) {
;     int key = task >> 2, g = task & 3;
;     int tok = tokf(key);
;     uint4 c0 = make_uint4(0, 0, 0, 0), c1 = c0;
;     if (tok >= 0) {
;       const u16* src = z + (size_t)tok * ld + col + g * 8;
; __device__ __forceinline__ void attnC_item(unsigned char* ws, int item, unsigned char* lds, int wv_) {
;   const u16* z = (const u16*)(ws + OFF_U);
;   const float* tb = (const float*)(ws + OFF_ROPE);
;   u16* O = (u16*)(ws + OFF_O);
;   int qb = item & 127; int t1 = item >> 7;
;   int kvh = t1 & 1, b = t1 >> 1;
;   const int i0 = qb * 16;
;   u16* Ks = (u16*)lds;
;   u16* Vt = (u16*)(lds + 288 * 128);
;   constexpr int NKP = 296;
;   auto tokf = [&](int key) -> int { int i = i0 - 128 + key; return (i >= 0 && i < SEQ_) ? (b * SEQ_ + i) : -1; };
;   __syncthreads();
;   stage_k(Ks, 288, tokf, z, CDC_, 1024 + kvh * 64, true, tb, wv_);
;   stage_vt(Vt, NKP, 288, tokf, z, CDC_, 1152 + kvh * 64, wv_);
.LBB0_466:
	s_lshl_b32 s2, s11, 4
	s_bfe_u32 s13, s11, 0x10007
	s_and_b32 s12, s2, 0x7f0
	s_waitcnt lgkmcnt(0)
	s_barrier
	s_waitcnt vmcnt(0)
	v_mbcnt_lo_u32_b32 v240, -1, 0
	v_mbcnt_hi_u32_b32 v240, -1, v240
	v_or_b32_e32 v240, s60, v240
	s_ashr_i32 s2, s11, 8
	s_lshl_b32 s2, s2, 11
	s_add_i32 s2, s2, s12
	s_add_i32 s2, s2, 0xffffff80
	v_lshrrev_b32_e32 v241, 1, v240
	v_add_u32_e32 v241, s2, v241
	s_bfe_u32 s3, s11, 0x10007
	s_lshl_b32 s3, s3, 7
	s_addk_i32 s3, 0x800
	v_and_b32_e32 v248, 1, v240
	v_lshl_add_u32 v248, v248, 8, s3
	v_mov_b32_e32 v249, 0
	v_lshl_add_u64 v[246:247], s[58:59], 0, v[248:249]
	v_mad_i64_i32 v[244:245], s[2:3], v241, s92, v[246:247]
	global_load_dword v242, v[244:245], off
	v_cmp_gt_u32_e32 vcc, 64, v240
	s_and_saveexec_b64 s[2:3], vcc
	s_cbranch_execz .Lpfc_skip
	v_mov_b32_e32 v248, 0x220000
	v_lshl_add_u64 v[244:245], v[244:245], 0, v[248:249]
	global_load_dword v243, v[244:245], off
.Lpfc_skip:
	s_or_b64 exec, exec, s[2:3]
	v_mbcnt_lo_u32_b32 v0, -1, 0
	v_mbcnt_hi_u32_b32 v0, -1, v0
	s_movk_i32 s2, 0x480
	v_or_b32_e32 v10, s60, v0
	s_ashr_i32 s8, s11, 8
	s_lshl_b32 s9, s13, 6
	v_cmp_gt_i32_e32 vcc, s2, v10
	s_and_saveexec_b64 s[2:3], vcc
	s_cbranch_execz .LBB0_471
	s_lshl_b32 s4, s9, 1
	s_add_u32 s4, s58, s4
	v_and_b32_e32 v11, 3, v0
	s_addc_u32 s5, s59, 0
	v_lshlrev_b32_e32 v166, 4, v11
	v_lshlrev_b32_e32 v12, 3, v11
	v_lshl_add_u64 v[8:9], s[4:5], 0, v[166:167]
	v_or_b32_e32 v13, 4, v11
	s_add_i32 s18, s12, 0xffffff80
	s_lshl_b32 s19, s8, 11
	s_mov_b64 s[4:5], 0
	s_branch .LBB0_469

; #define tidx() tidx_(wv_)
; template <typename TokF>
; __device__ __forceinline__ void stage_k(u16* Ks, int nk, TokF tokf, const u16* z, int ld, int col, bool rope, const float* tb, int wv_) {
;   for (int task = tidx(); task < nk * 4; task += NTHREADS) {
;     int key = task >> 2, g = task & 3;
;     int tok = tokf(key);
;     uint4 c0 = make_uint4(0, 0, 0, 0), c1 = c0;
;     if (tok >= 0) {
;       const u16* src = z + (size_t)tok * ld + col + g * 8;
; __device__ __forceinline__ void attnD_item(unsigned char* ws, int item, unsigned char* lds, int wv_) {
;   const u16* z = (const u16*)(ws + OFF_U);
;   u16* O = (u16*)(ws + OFF_O);
;   int rp = item & 15; int t1 = item >> 4;
;   int h = t1 & 15, b = t1 >> 4;
;   const int R0 = min(max(2 * rp - 4, 0), 24);
;   u16* Ks = (u16*)lds;
;   u16* Vt = (u16*)(lds + 576 * 128);
;   constexpr int NKP = 584;
;   float* rpb = (float*)(lds + 576 * 128 + 64 * NKP * 2);
;   auto tokf = [&](int key) -> int { int gr = R0 + (key >> 6); return (gr < 32) ? (b * SEQ_ + gr * 64 + (key & 63)) : -1; };
;   __syncthreads();
;   stage_k(Ks, 576, tokf, z, CDC_, 2304 + h * 64, false, nullptr, wv_);
;   stage_vt(Vt, NKP, 576, tokf, z, CDC_, 3328 + h * 64, wv_);
.LBB0_1275:
	s_lshl_b32 s2, s28, 1
	s_and_b32 s18, s2, 30
	v_sub_u32_e64 v0, s18, 4 clamp
	s_bfe_u32 s19, s28, 0x40004
	v_min_u32_e32 v12, 24, v0
	v_mbcnt_lo_u32_b32 v240, -1, 0
	v_mbcnt_hi_u32_b32 v240, -1, v240
	v_or_b32_e32 v240, s60, v240
	s_ashr_i32 s2, s28, 8
	s_lshl_b32 s2, s2, 11
	s_sub_i32 s3, s18, 4
	s_max_i32 s3, s3, 0
	s_min_i32 s3, s3, 24
	s_lshl_b32 s3, s3, 6
	s_add_i32 s2, s2, s3
	v_lshrrev_b32_e32 v241, 1, v240
	v_add_u32_e32 v241, s2, v241
	s_lshl_b32 s3, s19, 7
	s_addk_i32 s3, 0x1200
	v_and_b32_e32 v248, 1, v240
	v_lshl_add_u32 v248, v248, 11, s3
	v_mov_b32_e32 v249, 0
	v_lshl_add_u64 v[246:247], s[58:59], 0, v[248:249]
	v_mad_i64_i32 v[244:245], s[2:3], v241, s92, v[246:247]
	global_load_dword v242, v[244:245], off
	v_mov_b32_e32 v248, 0x220000
	v_lshl_add_u64 v[244:245], v[244:245], 0, v[248:249]
	global_load_dword v243, v[244:245], off
	v_cmp_gt_u32_e32 vcc, 0x80, v240
	s_and_saveexec_b64 s[2:3], vcc
	s_cbranch_execz .Lpfd_skip
	v_lshl_add_u64 v[244:245], v[244:245], 0, v[248:249]
	global_load_dword v242, v[244:245], off
.Lpfd_skip:
	s_or_b64 exec, exec, s[2:3]
	s_barrier
	v_mbcnt_lo_u32_b32 v0, -1, 0
	v_mbcnt_hi_u32_b32 v0, -1, v0
	s_movk_i32 s2, 0x900
	v_or_b32_e32 v10, s60, v0
	s_ashr_i32 s12, s28, 8
	s_lshl_b32 s13, s19, 6
	v_cmp_gt_i32_e32 vcc, s2, v10
	s_and_saveexec_b64 s[2:3], vcc
	s_cbranch_execz .LBB0_1280
	s_lshl_b32 s4, s13, 1
	s_add_u32 s4, s58, s4
	v_and_b32_e32 v11, 3, v0
	s_addc_u32 s5, s59, 0
	v_lshlrev_b32_e32 v166, 4, v11
	v_lshl_add_u64 v[0:1], s[4:5], 0, v[166:167]
	s_mov_b64 s[4:5], 0x1200
	v_lshl_add_u64 v[8:9], v[0:1], 0, s[4:5]
	v_or_b32_e32 v13, 4, v11
	s_lshl_b32 s8, s12, 11
	s_mov_b64 s[4:5], 0
	s_branch .LBB0_1278
